# attn K/V staging: 8 tile loads issued back to back, one wait
# baseline (speedup 1.0000x reference)
; #define LAS __attribute__((address_space(3)))
; template <class T> __device__ __forceinline__ T* at(const void* base, unsigned byteoff) { return (T*)((char*)base + byteoff); }
; __device__ __forceinline__ void attn_phase(LAS unsigned char* lds, const bf16_t* q, const bf16_t* kv, bf16_t* cat, const float* btab, const float* sinks, int tid, int G) {
;     ...
;         const int nbk = unit >> 1, n = nbk & 15, tok0 = nbk * 128, hku = unit & 1;
;         const float sink = sinks[hku * 4 + g] * LOG2E;
;         const LAS float* bp = btx + (hku * 4 + g) * 192 + 32 + (128 + l31 - 4 * hi) - 155;
;         __syncthreads();
; #pragma unroll
;         for (int i = 0; i < 4; ++i) {
;             const int c = tid + 512 * i, sj = c >> 3, ch = c & 7;
;             u32x4 kw = (u32x4){0u, 0u, 0u, 0u};
;             if (n > 0 || sj >= 128) kw = *at<const u32x4>(kv, (unsigned)((tok0 - 128 + sj) * 256 + hku * 64 + ch * 8) * 2u);
;             *(LAS u32x4*)(Ks + sj * 72 + ch * 8) = kw;
;         }
; #pragma unroll
;         for (int i = 0; i < 4; ++i) {
;             const int c = tid + 512 * i, sj = c & 255, ch = c >> 8;
;             u32x4 vw = (u32x4){0u, 0u, 0u, 0u};
;             if (n > 0 || sj >= 128) vw = *at<const u32x4>(kv, (unsigned)((tok0 - 128 + sj) * 256 + 128 + hku * 64 + ch * 8) * 2u);
.LBB0_532:
	s_and_b32 s23, s4, 1
	v_lshl_add_u32 v6, s23, 2, v83
	v_ashrrev_i32_e32 v7, 31, v6
	v_lshl_add_u64 v[0:1], v[6:7], 2, s[58:59]
	global_load_dword v7, v[0:1], off
	s_ashr_i32 s2, s4, 1
	s_and_b32 s30, s2, 15
	s_lshl_b32 s2, s2, 7
	s_cmp_lg_u32 s30, 0
	s_cselect_b64 s[28:29], -1, 0
	s_lshl_b32 s23, s23, 7
	s_add_i32 s22, s2, 0x7fff80
	v_or_b32_e32 v8, s23, v164
	s_or_b64 s[48:49], s[38:39], s[28:29]
	v_mov_b32_e32 v0, 0
	v_mov_b32_e32 v2, 0
	v_mov_b32_e32 v3, 0
	v_mov_b32_e32 v4, 0
	v_mov_b32_e32 v5, 0
	s_barrier
	v_mov_b32_e32 v16, 0
	v_mov_b32_e32 v17, 0
	v_mov_b32_e32 v18, 0
	v_mov_b32_e32 v19, 0
	v_mov_b32_e32 v20, 0
	v_mov_b32_e32 v21, 0
	v_mov_b32_e32 v22, 0
	v_mov_b32_e32 v23, 0
	v_mov_b32_e32 v24, 0
	v_mov_b32_e32 v25, 0
	v_mov_b32_e32 v26, 0
	v_mov_b32_e32 v27, 0
	v_mov_b32_e32 v28, 0
	v_mov_b32_e32 v29, 0
	v_mov_b32_e32 v30, 0
	v_mov_b32_e32 v31, 0
	v_mov_b32_e32 v32, 0
	v_mov_b32_e32 v33, 0
	v_mov_b32_e32 v34, 0
	v_mov_b32_e32 v35, 0
	v_mov_b32_e32 v36, 0
	v_mov_b32_e32 v37, 0
	v_mov_b32_e32 v38, 0
	v_mov_b32_e32 v39, 0
	v_mov_b32_e32 v40, 0
	v_mov_b32_e32 v41, 0
	v_mov_b32_e32 v42, 0
	v_mov_b32_e32 v43, 0
	v_mov_b32_e32 v44, 0
	v_mov_b32_e32 v45, 0
	v_mov_b32_e32 v46, 0
	v_mov_b32_e32 v47, 0
	s_and_saveexec_b64 s[46:47], s[48:49]
	s_cbranch_execz .Lattn_stage_k0
	v_add_u32_e32 v1, s22, v170
	v_lshl_or_b32 v1, v1, 9, v8
	global_load_dwordx4 v[16:19], v1, s[54:55]
.Lattn_stage_k0:
	s_or_b64 exec, exec, s[46:47]
	s_or_b64 s[48:49], s[28:29], s[40:41]
	s_and_saveexec_b64 s[46:47], s[48:49]
	s_cbranch_execz .Lattn_stage_k1
	v_add_u32_e32 v1, s22, v171
	v_lshl_or_b32 v1, v1, 9, v8
	global_load_dwordx4 v[20:23], v1, s[54:55]
.Lattn_stage_k1:
	s_or_b64 exec, exec, s[46:47]
	s_or_b64 s[48:49], s[28:29], s[42:43]
	s_and_saveexec_b64 s[46:47], s[48:49]
	s_cbranch_execz .Lattn_stage_k2
	v_add_u32_e32 v1, s22, v172
	v_lshl_or_b32 v1, v1, 9, v8
	global_load_dwordx4 v[24:27], v1, s[54:55]
.Lattn_stage_k2:
	s_or_b64 exec, exec, s[46:47]
	s_or_b64 s[48:49], s[28:29], s[44:45]
	s_and_saveexec_b64 s[46:47], s[48:49]
	s_cbranch_execz .Lattn_stage_k3
	v_add_u32_e32 v1, s22, v173
	v_lshl_or_b32 v1, v1, 9, v8
	global_load_dwordx4 v[28:31], v1, s[54:55]
.Lattn_stage_k3:
	s_or_b64 exec, exec, s[46:47]
	v_add_u32_e32 v1, s22, v165
	v_lshl_or_b32 v1, v1, 9, s23
	s_or_b64 s[28:29], s[28:29], s[36:37]
	v_or_b32_e32 v8, 0x100, v1
	s_and_saveexec_b64 s[46:47], s[28:29]
	s_cbranch_execz .Lattn_stage_v
	v_add_u32_e32 v0, v8, v174
	global_load_dwordx4 v[32:35], v0, s[54:55]
	v_add_u32_e32 v0, v8, v175
	global_load_dwordx4 v[36:39], v0, s[54:55]
	v_add_u32_e32 v0, v8, v176
	global_load_dwordx4 v[40:43], v0, s[54:55]
	v_add_u32_e32 v0, v8, v177
	global_load_dwordx4 v[44:47], v0, s[54:55]
; #define LAS __attribute__((address_space(3)))
; template <class T> __device__ __forceinline__ T* at(const void* base, unsigned byteoff) { return (T*)((char*)base + byteoff); }
; __device__ __forceinline__ void attn_phase(LAS unsigned char* lds, const bf16_t* q, const bf16_t* kv, bf16_t* cat, const float* btab, const float* sinks, int tid, int G) {
;     ...
;         const float sink = sinks[hku * 4 + g] * LOG2E;
;         const LAS float* bp = btx + (hku * 4 + g) * 192 + 32 + (128 + l31 - 4 * hi) - 155;
;         __syncthreads();
; #pragma unroll
;         for (int i = 0; i < 4; ++i) {
;             const int c = tid + 512 * i, sj = c >> 3, ch = c & 7;
;             u32x4 kw = (u32x4){0u, 0u, 0u, 0u};
;             if (n > 0 || sj >= 128) kw = *at<const u32x4>(kv, (unsigned)((tok0 - 128 + sj) * 256 + hku * 64 + ch * 8) * 2u);
;             *(LAS u32x4*)(Ks + sj * 72 + ch * 8) = kw;
;         }
; #pragma unroll
;         for (int i = 0; i < 4; ++i) {
;             const int c = tid + 512 * i, sj = c & 255, ch = c >> 8;
;             u32x4 vw = (u32x4){0u, 0u, 0u, 0u};
;             if (n > 0 || sj >= 128) vw = *at<const u32x4>(kv, (unsigned)((tok0 - 128 + sj) * 256 + 128 + hku * 64 + ch * 8) * 2u);
; #pragma unroll
;             for (int e = 0; e < 8; ++e) Vt[(ch * 8 + e) * 264 + sj] = (bf16_t)(vw[e >> 1] >> (16 * (e & 1)));
;         }
;         __syncthreads();
.Lattn_stage_v:
	s_or_b64 exec, exec, s[46:47]
	s_mov_b32 s31, 0
	s_movk_i32 s22, 0x300
	v_mad_u64_u32 v[4:5], s[22:23], v6, s22, v[82:83]
	s_waitcnt vmcnt(0)
	v_mul_f32_e32 v203, 0x3fb8aa3b, v7
	ds_write_b128 v179, v[16:19]
	ds_write_b128 v180, v[20:23]
	ds_write_b128 v181, v[24:27]
	ds_write_b128 v198, v[28:31]
	ds_write_b16 v199, v32 offset:36864
	ds_write_b16_d16_hi v199, v32 offset:37392
	ds_write_b16 v199, v33 offset:37920
	ds_write_b16_d16_hi v199, v33 offset:38448
	ds_write_b16 v199, v34 offset:38976
	ds_write_b16_d16_hi v199, v34 offset:39504
	ds_write_b16 v199, v35 offset:40032
	ds_write_b16_d16_hi v199, v35 offset:40560
	ds_write_b16 v200, v36 offset:36864
	ds_write_b16_d16_hi v200, v36 offset:37392
	ds_write_b16 v200, v37 offset:37920
	ds_write_b16_d16_hi v200, v37 offset:38448
	ds_write_b16 v200, v38 offset:38976
	ds_write_b16_d16_hi v200, v38 offset:39504
	ds_write_b16 v200, v39 offset:40032
	ds_write_b16_d16_hi v200, v39 offset:40560
	ds_write_b16 v201, v40 offset:36864
	ds_write_b16_d16_hi v201, v40 offset:37392
	ds_write_b16 v201, v41 offset:37920
	ds_write_b16_d16_hi v201, v41 offset:38448
	ds_write_b16 v201, v42 offset:38976
	ds_write_b16_d16_hi v201, v42 offset:39504
	ds_write_b16 v201, v43 offset:40032
	ds_write_b16_d16_hi v201, v43 offset:40560
	ds_write_b16 v202, v44 offset:36864
	ds_write_b16_d16_hi v202, v44 offset:37392
	ds_write_b16 v202, v45 offset:37920
	ds_write_b16_d16_hi v202, v45 offset:38448
	ds_write_b16 v202, v46 offset:38976
	ds_write_b16_d16_hi v202, v46 offset:39504
	ds_write_b16 v202, v47 offset:40032
	ds_write_b16_d16_hi v202, v47 offset:40560
	v_add_u32_e32 v0, 0xfffffe14, v4
	s_waitcnt lgkmcnt(0)
	s_barrier
	v_lshlrev_b32_e32 v1, 7, v6
	v_add_u32_e32 v2, -4, v4
	v_add_u32_e32 v3, -12, v4
	v_subrev_u32_e32 v5, 36, v4
	v_subrev_u32_e32 v6, 44, v4
	v_add_u32_e32 v7, 0xffffffbc, v4
	v_add_u32_e32 v8, 0xffffffb4, v4
	v_add_u32_e32 v9, 0xffffff9c, v4
	v_add_u32_e32 v10, 0xffffff94, v4
	v_add_u32_e32 v11, 0xffffff7c, v4
	v_add_u32_e32 v12, 0xffffff74, v4
	v_add_u32_e32 v13, 0xffffff5c, v4
	v_add_u32_e32 v14, 0xffffff54, v4
	v_add_u32_e32 v15, 0xffffff3c, v4
	v_add_u32_e32 v16, 0xffffff34, v4
	v_add_u32_e32 v17, 0xffffff1c, v4
	v_add_u32_e32 v18, 0xffffff14, v4
	v_add_u32_e32 v19, 0xfffffefc, v4
	v_add_u32_e32 v20, 0xfffffef4, v4
	v_add_u32_e32 v21, 0xfffffedc, v4
	v_add_u32_e32 v22, 0xfffffed4, v4
	v_add_u32_e32 v23, 0xfffffebc, v4
	v_add_u32_e32 v24, 0xfffffeb4, v4
	v_add_u32_e32 v25, 0xfffffe9c, v4
	v_add_u32_e32 v26, 0xfffffe94, v4
	v_add_u32_e32 v27, 0xfffffe7c, v4
	v_add_u32_e32 v28, 0xfffffe74, v4
	v_add_u32_e32 v29, 0xfffffe5c, v4
	v_add_u32_e32 v30, 0xfffffe54, v4
	v_add_u32_e32 v31, 0xfffffe3c, v4
	v_add_u32_e32 v32, 0xfffffe34, v4
	v_add_u32_e32 v33, 0xfffffe1c, v4
	ds_read2_b32 v[84:85], v4 offset0:31 offset1:32
	ds_read2_b32 v[86:87], v4 offset0:29 offset1:30
	ds_read2_b32 v[88:89], v4 offset0:23 offset1:24
	ds_read2_b32 v[90:91], v4 offset0:21 offset1:22
	ds_read2_b32 v[92:93], v4 offset0:15 offset1:16
	ds_read2_b32 v[94:95], v4 offset0:13 offset1:14
	ds_read2_b32 v[96:97], v4 offset0:7 offset1:8
	ds_read2_b32 v[98:99], v4 offset0:5 offset1:6
	ds_read2_b32 v[100:101], v6 offset1:1
	ds_read2_b32 v[102:103], v7 offset1:1
	ds_read2_b32 v[104:105], v8 offset1:1
	ds_read2_b32 v[106:107], v9 offset1:1
	ds_read2_b32 v[108:109], v10 offset1:1
	ds_read2_b32 v[110:111], v11 offset1:1
	ds_read2_b32 v[112:113], v12 offset1:1
	ds_read2_b32 v[114:115], v13 offset1:1
	ds_read2_b32 v[116:117], v14 offset1:1
	ds_read2_b32 v[118:119], v15 offset1:1
	ds_read2_b32 v[120:121], v16 offset1:1
	ds_read2_b32 v[122:123], v17 offset1:1
	ds_read2_b32 v[124:125], v18 offset1:1
	ds_read2_b32 v[126:127], v19 offset1:1
	ds_read2_b32 v[128:129], v20 offset1:1
	ds_read2_b32 v[130:131], v21 offset1:1
	ds_read2_b32 v[132:133], v22 offset1:1
	ds_read2_b32 v[134:135], v23 offset1:1
	ds_read2_b32 v[136:137], v24 offset1:1
	ds_read2_b32 v[138:139], v25 offset1:1
	ds_read2_b32 v[140:141], v26 offset1:1
	ds_read2_b32 v[142:143], v27 offset1:1
	ds_read2_b32 v[144:145], v28 offset1:1
	ds_read2_b32 v[146:147], v29 offset1:1
	ds_read2_b32 v[148:149], v30 offset1:1
	ds_read2_b32 v[150:151], v31 offset1:1
	ds_read2_b32 v[152:153], v32 offset1:1
	ds_read2_b32 v[154:155], v33 offset1:1
	ds_read2_b32 v[156:157], v2 offset1:1
	ds_read2_b32 v[158:159], v3 offset1:1
	ds_read2_b32 v[160:161], v5 offset1:1
	ds_read2_b32 v[162:163], v0 offset1:1
	s_cmp_eq_u32 s30, 0
	v_or_b32_e32 v0, s30, v166
	v_or_b32_e32 v204, s2, v81
	v_or_b32_e32 v205, v1, v167
	s_cselect_b64 s[46:47], -1, 0
	v_or_b32_e32 v206, v1, v169
	v_cmp_eq_u32_e64 s[48:49], 0, v0
	s_mov_b64 s[60:61], -1
